# stack + grid-barrier poll interval s_sleep 4 -> 1 (24 spin sites)
# speedup vs baseline: 1.0131x; 1.0131x over previous
; __device__ __forceinline__ unsigned xb_ld(unsigned* p)              { return __hip_atomic_load(p, __ATOMIC_RELAXED, __HIP_MEMORY_SCOPE_AGENT); }
; __device__ __forceinline__ unsigned xb_add(unsigned* p, unsigned v) { return __hip_atomic_fetch_add(p, v, __ATOMIC_RELAXED, __HIP_MEMORY_SCOPE_AGENT); }
; #define XB_SPIN(cond, bar) do { unsigned _sp = 0; while (cond) { __builtin_amdgcn_s_sleep(4); \
;     if ((++_sp & 255u) == 0u) { if (xb_ld(&(bar)[XB_TMO])) break; if (_sp > XB_SPIN_CAP) { atomicAdd(&(bar)[XB_TMO], 1u); break; } } } } while (0)
; __device__ __forceinline__ void xcd_barrier(const XcdBarrier& b, const bool t0) {
;     ...
;             else XB_SPIN(xb_ld(&bar[XB_TOPGEN]) == tg, bar);
;             __builtin_amdgcn_fence(__ATOMIC_ACQUIRE, "agent");
;             xb_add(&bar[XB_XGEN(b.x)], 1u);
;             asm volatile("s_waitcnt vmcnt(0)" ::: "memory");
;         } else {
;             XB_SPIN(xb_ld(&bar[XB_XGEN(b.x)]) == gen, bar);
.LBB0_180:
	s_and_b32 s22, s21, 0xff
	s_mov_b64 s[36:37], -1
	s_cmp_lg_u32 s22, 0
	s_mov_b64 s[40:41], -1
	s_sleep 1
	s_cbranch_scc0 .LBB0_183
	s_and_b64 vcc, exec, s[40:41]
	s_cbranch_vccz .LBB0_179

; __device__ __forceinline__ unsigned xb_ld(unsigned* p)              { return __hip_atomic_load(p, __ATOMIC_RELAXED, __HIP_MEMORY_SCOPE_AGENT); }
; __device__ __forceinline__ unsigned xb_add(unsigned* p, unsigned v) { return __hip_atomic_fetch_add(p, v, __ATOMIC_RELAXED, __HIP_MEMORY_SCOPE_AGENT); }
; #define XB_SPIN(cond, bar) do { unsigned _sp = 0; while (cond) { __builtin_amdgcn_s_sleep(4); \
;     if ((++_sp & 255u) == 0u) { if (xb_ld(&(bar)[XB_TMO])) break; if (_sp > XB_SPIN_CAP) { atomicAdd(&(bar)[XB_TMO], 1u); break; } } } } while (0)
; __device__ __forceinline__ void xcd_barrier(const XcdBarrier& b, const bool t0) {
;     ...
;             else XB_SPIN(xb_ld(&bar[XB_TOPGEN]) == tg, bar);
;             __builtin_amdgcn_fence(__ATOMIC_ACQUIRE, "agent");
;             xb_add(&bar[XB_XGEN(b.x)], 1u);
;             asm volatile("s_waitcnt vmcnt(0)" ::: "memory");
;         } else {
;             XB_SPIN(xb_ld(&bar[XB_XGEN(b.x)]) == gen, bar);
.LBB0_197:
	s_and_b32 s22, s21, 0xff
	s_cmp_lg_u32 s22, 0
	s_mov_b64 s[36:37], -1
	s_sleep 1
	s_cbranch_scc0 .LBB0_200
	s_mov_b64 s[38:39], -1
	s_and_b64 vcc, exec, s[36:37]
	s_cbranch_vccz .LBB0_196

; __device__ __forceinline__ unsigned xb_ld(unsigned* p)              { return __hip_atomic_load(p, __ATOMIC_RELAXED, __HIP_MEMORY_SCOPE_AGENT); }
; __device__ __forceinline__ unsigned xb_add(unsigned* p, unsigned v) { return __hip_atomic_fetch_add(p, v, __ATOMIC_RELAXED, __HIP_MEMORY_SCOPE_AGENT); }
; #define XB_SPIN(cond, bar) do { unsigned _sp = 0; while (cond) { __builtin_amdgcn_s_sleep(4); \
;     if ((++_sp & 255u) == 0u) { if (xb_ld(&(bar)[XB_TMO])) break; if (_sp > XB_SPIN_CAP) { atomicAdd(&(bar)[XB_TMO], 1u); break; } } } } while (0)
; __device__ __forceinline__ void xcd_barrier(const XcdBarrier& b, const bool t0) {
;     ...
;             else XB_SPIN(xb_ld(&bar[XB_TOPGEN]) == tg, bar);
;             __builtin_amdgcn_fence(__ATOMIC_ACQUIRE, "agent");
;             xb_add(&bar[XB_XGEN(b.x)], 1u);
;             asm volatile("s_waitcnt vmcnt(0)" ::: "memory");
;         } else {
;             XB_SPIN(xb_ld(&bar[XB_XGEN(b.x)]) == gen, bar);
.LBB0_259:
	s_and_b32 s25, s21, 0xff
	s_mov_b64 s[36:37], -1
	s_cmp_lg_u32 s25, 0
	s_mov_b64 s[40:41], -1
	s_sleep 1
	s_cbranch_scc0 .LBB0_262
	s_and_b64 vcc, exec, s[40:41]
	s_cbranch_vccz .LBB0_258

; __device__ __forceinline__ unsigned xb_ld(unsigned* p)              { return __hip_atomic_load(p, __ATOMIC_RELAXED, __HIP_MEMORY_SCOPE_AGENT); }
; __device__ __forceinline__ unsigned xb_add(unsigned* p, unsigned v) { return __hip_atomic_fetch_add(p, v, __ATOMIC_RELAXED, __HIP_MEMORY_SCOPE_AGENT); }
; #define XB_SPIN(cond, bar) do { unsigned _sp = 0; while (cond) { __builtin_amdgcn_s_sleep(4); \
;     if ((++_sp & 255u) == 0u) { if (xb_ld(&(bar)[XB_TMO])) break; if (_sp > XB_SPIN_CAP) { atomicAdd(&(bar)[XB_TMO], 1u); break; } } } } while (0)
; __device__ __forceinline__ void xcd_barrier(const XcdBarrier& b, const bool t0) {
;     ...
;             else XB_SPIN(xb_ld(&bar[XB_TOPGEN]) == tg, bar);
;             __builtin_amdgcn_fence(__ATOMIC_ACQUIRE, "agent");
;             xb_add(&bar[XB_XGEN(b.x)], 1u);
;             asm volatile("s_waitcnt vmcnt(0)" ::: "memory");
;         } else {
;             XB_SPIN(xb_ld(&bar[XB_XGEN(b.x)]) == gen, bar);
.LBB0_276:
	s_and_b32 s25, s21, 0xff
	s_cmp_lg_u32 s25, 0
	s_mov_b64 s[36:37], -1
	s_sleep 1
	s_cbranch_scc0 .LBB0_279
	s_mov_b64 s[38:39], -1
	s_and_b64 vcc, exec, s[36:37]
	s_cbranch_vccz .LBB0_275

; __device__ __forceinline__ unsigned xb_ld(unsigned* p)              { return __hip_atomic_load(p, __ATOMIC_RELAXED, __HIP_MEMORY_SCOPE_AGENT); }
; __device__ __forceinline__ unsigned xb_add(unsigned* p, unsigned v) { return __hip_atomic_fetch_add(p, v, __ATOMIC_RELAXED, __HIP_MEMORY_SCOPE_AGENT); }
; #define XB_SPIN(cond, bar) do { unsigned _sp = 0; while (cond) { __builtin_amdgcn_s_sleep(4); \
;     if ((++_sp & 255u) == 0u) { if (xb_ld(&(bar)[XB_TMO])) break; if (_sp > XB_SPIN_CAP) { atomicAdd(&(bar)[XB_TMO], 1u); break; } } } } while (0)
; __device__ __forceinline__ void xcd_barrier(const XcdBarrier& b, const bool t0) {
;     ...
;             else XB_SPIN(xb_ld(&bar[XB_TOPGEN]) == tg, bar);
;             __builtin_amdgcn_fence(__ATOMIC_ACQUIRE, "agent");
;             xb_add(&bar[XB_XGEN(b.x)], 1u);
;             asm volatile("s_waitcnt vmcnt(0)" ::: "memory");
;         } else {
;             XB_SPIN(xb_ld(&bar[XB_XGEN(b.x)]) == gen, bar);
.LBB0_359:
	s_and_b32 s7, s6, 0xff
	s_mov_b64 s[38:39], -1
	s_cmp_lg_u32 s7, 0
	s_mov_b64 s[42:43], -1
	s_sleep 1
	s_cbranch_scc0 .LBB0_362
	s_and_b64 vcc, exec, s[42:43]
	s_cbranch_vccz .LBB0_358

; __device__ __forceinline__ unsigned xb_ld(unsigned* p)              { return __hip_atomic_load(p, __ATOMIC_RELAXED, __HIP_MEMORY_SCOPE_AGENT); }
; __device__ __forceinline__ unsigned xb_add(unsigned* p, unsigned v) { return __hip_atomic_fetch_add(p, v, __ATOMIC_RELAXED, __HIP_MEMORY_SCOPE_AGENT); }
; #define XB_SPIN(cond, bar) do { unsigned _sp = 0; while (cond) { __builtin_amdgcn_s_sleep(4); \
;     if ((++_sp & 255u) == 0u) { if (xb_ld(&(bar)[XB_TMO])) break; if (_sp > XB_SPIN_CAP) { atomicAdd(&(bar)[XB_TMO], 1u); break; } } } } while (0)
; __device__ __forceinline__ void xcd_barrier(const XcdBarrier& b, const bool t0) {
;     ...
;             else XB_SPIN(xb_ld(&bar[XB_TOPGEN]) == tg, bar);
;             __builtin_amdgcn_fence(__ATOMIC_ACQUIRE, "agent");
;             xb_add(&bar[XB_XGEN(b.x)], 1u);
;             asm volatile("s_waitcnt vmcnt(0)" ::: "memory");
;         } else {
;             XB_SPIN(xb_ld(&bar[XB_XGEN(b.x)]) == gen, bar);
.LBB0_376:
	s_and_b32 s7, s6, 0xff
	s_cmp_lg_u32 s7, 0
	s_mov_b64 s[38:39], -1
	s_sleep 1
	s_cbranch_scc0 .LBB0_379
	s_mov_b64 s[40:41], -1
	s_and_b64 vcc, exec, s[38:39]
	s_cbranch_vccz .LBB0_375

; __device__ __forceinline__ unsigned xb_ld(unsigned* p)              { return __hip_atomic_load(p, __ATOMIC_RELAXED, __HIP_MEMORY_SCOPE_AGENT); }
; __device__ __forceinline__ unsigned xb_add(unsigned* p, unsigned v) { return __hip_atomic_fetch_add(p, v, __ATOMIC_RELAXED, __HIP_MEMORY_SCOPE_AGENT); }
; #define XB_SPIN(cond, bar) do { unsigned _sp = 0; while (cond) { __builtin_amdgcn_s_sleep(4); \
;     if ((++_sp & 255u) == 0u) { if (xb_ld(&(bar)[XB_TMO])) break; if (_sp > XB_SPIN_CAP) { atomicAdd(&(bar)[XB_TMO], 1u); break; } } } } while (0)
; __device__ __forceinline__ void xcd_barrier(const XcdBarrier& b, const bool t0) {
;     ...
;             else XB_SPIN(xb_ld(&bar[XB_TOPGEN]) == tg, bar);
;             __builtin_amdgcn_fence(__ATOMIC_ACQUIRE, "agent");
;             xb_add(&bar[XB_XGEN(b.x)], 1u);
;             asm volatile("s_waitcnt vmcnt(0)" ::: "memory");
;         } else {
;             XB_SPIN(xb_ld(&bar[XB_XGEN(b.x)]) == gen, bar);
.LBB0_821:
	s_and_b32 s7, s6, 0xff
	s_mov_b64 s[40:41], -1
	s_cmp_lg_u32 s7, 0
	s_mov_b64 s[44:45], -1
	s_sleep 1
	s_cbranch_scc0 .LBB0_824
	s_and_b64 vcc, exec, s[44:45]
	s_cbranch_vccz .LBB0_820

; __device__ __forceinline__ unsigned xb_ld(unsigned* p)              { return __hip_atomic_load(p, __ATOMIC_RELAXED, __HIP_MEMORY_SCOPE_AGENT); }
; __device__ __forceinline__ unsigned xb_add(unsigned* p, unsigned v) { return __hip_atomic_fetch_add(p, v, __ATOMIC_RELAXED, __HIP_MEMORY_SCOPE_AGENT); }
; #define XB_SPIN(cond, bar) do { unsigned _sp = 0; while (cond) { __builtin_amdgcn_s_sleep(4); \
;     if ((++_sp & 255u) == 0u) { if (xb_ld(&(bar)[XB_TMO])) break; if (_sp > XB_SPIN_CAP) { atomicAdd(&(bar)[XB_TMO], 1u); break; } } } } while (0)
; __device__ __forceinline__ void xcd_barrier(const XcdBarrier& b, const bool t0) {
;     ...
;             else XB_SPIN(xb_ld(&bar[XB_TOPGEN]) == tg, bar);
;             __builtin_amdgcn_fence(__ATOMIC_ACQUIRE, "agent");
;             xb_add(&bar[XB_XGEN(b.x)], 1u);
;             asm volatile("s_waitcnt vmcnt(0)" ::: "memory");
;         } else {
;             XB_SPIN(xb_ld(&bar[XB_XGEN(b.x)]) == gen, bar);
.LBB0_838:
	s_and_b32 s7, s6, 0xff
	s_cmp_lg_u32 s7, 0
	s_mov_b64 s[40:41], -1
	s_sleep 1
	s_cbranch_scc0 .LBB0_841
	s_mov_b64 s[42:43], -1
	s_and_b64 vcc, exec, s[40:41]
	s_cbranch_vccz .LBB0_837

; __device__ __forceinline__ unsigned xb_ld(unsigned* p)              { return __hip_atomic_load(p, __ATOMIC_RELAXED, __HIP_MEMORY_SCOPE_AGENT); }
; __device__ __forceinline__ unsigned xb_add(unsigned* p, unsigned v) { return __hip_atomic_fetch_add(p, v, __ATOMIC_RELAXED, __HIP_MEMORY_SCOPE_AGENT); }
; #define XB_SPIN(cond, bar) do { unsigned _sp = 0; while (cond) { __builtin_amdgcn_s_sleep(4); \
;     if ((++_sp & 255u) == 0u) { if (xb_ld(&(bar)[XB_TMO])) break; if (_sp > XB_SPIN_CAP) { atomicAdd(&(bar)[XB_TMO], 1u); break; } } } } while (0)
; __device__ __forceinline__ void xcd_barrier(const XcdBarrier& b, const bool t0) {
;     ...
;             else XB_SPIN(xb_ld(&bar[XB_TOPGEN]) == tg, bar);
;             __builtin_amdgcn_fence(__ATOMIC_ACQUIRE, "agent");
;             xb_add(&bar[XB_XGEN(b.x)], 1u);
;             asm volatile("s_waitcnt vmcnt(0)" ::: "memory");
;         } else {
;             XB_SPIN(xb_ld(&bar[XB_XGEN(b.x)]) == gen, bar);
.LBB0_1044:
	s_and_b32 s7, s6, 0xff
	s_mov_b64 s[36:37], -1
	s_cmp_lg_u32 s7, 0
	s_mov_b64 s[40:41], -1
	s_sleep 1
	s_cbranch_scc0 .LBB0_1047
	s_and_b64 vcc, exec, s[40:41]
	s_cbranch_vccz .LBB0_1043

; __device__ __forceinline__ unsigned xb_ld(unsigned* p)              { return __hip_atomic_load(p, __ATOMIC_RELAXED, __HIP_MEMORY_SCOPE_AGENT); }
; __device__ __forceinline__ unsigned xb_add(unsigned* p, unsigned v) { return __hip_atomic_fetch_add(p, v, __ATOMIC_RELAXED, __HIP_MEMORY_SCOPE_AGENT); }
; #define XB_SPIN(cond, bar) do { unsigned _sp = 0; while (cond) { __builtin_amdgcn_s_sleep(4); \
;     if ((++_sp & 255u) == 0u) { if (xb_ld(&(bar)[XB_TMO])) break; if (_sp > XB_SPIN_CAP) { atomicAdd(&(bar)[XB_TMO], 1u); break; } } } } while (0)
; __device__ __forceinline__ void xcd_barrier(const XcdBarrier& b, const bool t0) {
;     ...
;             else XB_SPIN(xb_ld(&bar[XB_TOPGEN]) == tg, bar);
;             __builtin_amdgcn_fence(__ATOMIC_ACQUIRE, "agent");
;             xb_add(&bar[XB_XGEN(b.x)], 1u);
;             asm volatile("s_waitcnt vmcnt(0)" ::: "memory");
;         } else {
;             XB_SPIN(xb_ld(&bar[XB_XGEN(b.x)]) == gen, bar);
.LBB0_1061:
	s_and_b32 s7, s6, 0xff
	s_cmp_lg_u32 s7, 0
	s_mov_b64 s[36:37], -1
	s_sleep 1
	s_cbranch_scc0 .LBB0_1064
	s_mov_b64 s[38:39], -1
	s_and_b64 vcc, exec, s[36:37]
	s_cbranch_vccz .LBB0_1060

; __device__ __forceinline__ unsigned xb_ld(unsigned* p)              { return __hip_atomic_load(p, __ATOMIC_RELAXED, __HIP_MEMORY_SCOPE_AGENT); }
; __device__ __forceinline__ unsigned xb_add(unsigned* p, unsigned v) { return __hip_atomic_fetch_add(p, v, __ATOMIC_RELAXED, __HIP_MEMORY_SCOPE_AGENT); }
; #define XB_SPIN(cond, bar) do { unsigned _sp = 0; while (cond) { __builtin_amdgcn_s_sleep(4); \
;     if ((++_sp & 255u) == 0u) { if (xb_ld(&(bar)[XB_TMO])) break; if (_sp > XB_SPIN_CAP) { atomicAdd(&(bar)[XB_TMO], 1u); break; } } } } while (0)
; __device__ __forceinline__ void xcd_barrier(const XcdBarrier& b, const bool t0) {
;     ...
;             else XB_SPIN(xb_ld(&bar[XB_TOPGEN]) == tg, bar);
;             __builtin_amdgcn_fence(__ATOMIC_ACQUIRE, "agent");
;             xb_add(&bar[XB_XGEN(b.x)], 1u);
;             asm volatile("s_waitcnt vmcnt(0)" ::: "memory");
;         } else {
;             XB_SPIN(xb_ld(&bar[XB_XGEN(b.x)]) == gen, bar);
.LBB0_1367:
	s_and_b32 s7, s6, 0xff
	s_mov_b64 s[34:35], -1
	s_cmp_lg_u32 s7, 0
	s_mov_b64 s[38:39], -1
	s_sleep 1
	s_cbranch_scc0 .LBB0_1370
	s_and_b64 vcc, exec, s[38:39]
	s_cbranch_vccz .LBB0_1366

; __device__ __forceinline__ unsigned xb_ld(unsigned* p)              { return __hip_atomic_load(p, __ATOMIC_RELAXED, __HIP_MEMORY_SCOPE_AGENT); }
; __device__ __forceinline__ unsigned xb_add(unsigned* p, unsigned v) { return __hip_atomic_fetch_add(p, v, __ATOMIC_RELAXED, __HIP_MEMORY_SCOPE_AGENT); }
; #define XB_SPIN(cond, bar) do { unsigned _sp = 0; while (cond) { __builtin_amdgcn_s_sleep(4); \
;     if ((++_sp & 255u) == 0u) { if (xb_ld(&(bar)[XB_TMO])) break; if (_sp > XB_SPIN_CAP) { atomicAdd(&(bar)[XB_TMO], 1u); break; } } } } while (0)
; __device__ __forceinline__ void xcd_barrier(const XcdBarrier& b, const bool t0) {
;     ...
;             else XB_SPIN(xb_ld(&bar[XB_TOPGEN]) == tg, bar);
;             __builtin_amdgcn_fence(__ATOMIC_ACQUIRE, "agent");
;             xb_add(&bar[XB_XGEN(b.x)], 1u);
;             asm volatile("s_waitcnt vmcnt(0)" ::: "memory");
;         } else {
;             XB_SPIN(xb_ld(&bar[XB_XGEN(b.x)]) == gen, bar);
.LBB0_1384:
	s_and_b32 s7, s6, 0xff
	s_cmp_lg_u32 s7, 0
	s_mov_b64 s[34:35], -1
	s_sleep 1
	s_cbranch_scc0 .LBB0_1387
	s_mov_b64 s[36:37], -1
	s_and_b64 vcc, exec, s[34:35]
	s_cbranch_vccz .LBB0_1383

; __device__ __forceinline__ unsigned xb_ld(unsigned* p)              { return __hip_atomic_load(p, __ATOMIC_RELAXED, __HIP_MEMORY_SCOPE_AGENT); }
; __device__ __forceinline__ unsigned xb_add(unsigned* p, unsigned v) { return __hip_atomic_fetch_add(p, v, __ATOMIC_RELAXED, __HIP_MEMORY_SCOPE_AGENT); }
; #define XB_SPIN(cond, bar) do { unsigned _sp = 0; while (cond) { __builtin_amdgcn_s_sleep(4); \
;     if ((++_sp & 255u) == 0u) { if (xb_ld(&(bar)[XB_TMO])) break; if (_sp > XB_SPIN_CAP) { atomicAdd(&(bar)[XB_TMO], 1u); break; } } } } while (0)
; __device__ __forceinline__ void xcd_barrier(const XcdBarrier& b, const bool t0) {
;     ...
;             else XB_SPIN(xb_ld(&bar[XB_TOPGEN]) == tg, bar);
;             __builtin_amdgcn_fence(__ATOMIC_ACQUIRE, "agent");
;             xb_add(&bar[XB_XGEN(b.x)], 1u);
;             asm volatile("s_waitcnt vmcnt(0)" ::: "memory");
;         } else {
;             XB_SPIN(xb_ld(&bar[XB_XGEN(b.x)]) == gen, bar);
.LBB0_1468:
	s_and_b32 s7, s6, 0xff
	s_mov_b64 s[30:31], -1
	s_cmp_lg_u32 s7, 0
	s_mov_b64 s[36:37], -1
	s_sleep 1
	s_cbranch_scc0 .LBB0_1471
	s_and_b64 vcc, exec, s[36:37]
	s_cbranch_vccz .LBB0_1467

; __device__ __forceinline__ unsigned xb_ld(unsigned* p)              { return __hip_atomic_load(p, __ATOMIC_RELAXED, __HIP_MEMORY_SCOPE_AGENT); }
; __device__ __forceinline__ unsigned xb_add(unsigned* p, unsigned v) { return __hip_atomic_fetch_add(p, v, __ATOMIC_RELAXED, __HIP_MEMORY_SCOPE_AGENT); }
; #define XB_SPIN(cond, bar) do { unsigned _sp = 0; while (cond) { __builtin_amdgcn_s_sleep(4); \
;     if ((++_sp & 255u) == 0u) { if (xb_ld(&(bar)[XB_TMO])) break; if (_sp > XB_SPIN_CAP) { atomicAdd(&(bar)[XB_TMO], 1u); break; } } } } while (0)
; __device__ __forceinline__ void xcd_barrier(const XcdBarrier& b, const bool t0) {
;     ...
;             else XB_SPIN(xb_ld(&bar[XB_TOPGEN]) == tg, bar);
;             __builtin_amdgcn_fence(__ATOMIC_ACQUIRE, "agent");
;             xb_add(&bar[XB_XGEN(b.x)], 1u);
;             asm volatile("s_waitcnt vmcnt(0)" ::: "memory");
;         } else {
;             XB_SPIN(xb_ld(&bar[XB_XGEN(b.x)]) == gen, bar);
.LBB0_1485:
	s_and_b32 s7, s6, 0xff
	s_cmp_lg_u32 s7, 0
	s_mov_b64 s[30:31], -1
	s_sleep 1
	s_cbranch_scc0 .LBB0_1488
	s_mov_b64 s[34:35], -1
	s_and_b64 vcc, exec, s[30:31]
	s_cbranch_vccz .LBB0_1484
